# ring-4 variant with tiles loaded one half-step further ahead (publish waits vmcnt(2))
# baseline (speedup 1.0000x reference)
; DI int lane_id() { int l; asm volatile("v_mbcnt_lo_u32_b32 %0, -1, 0\n\tv_mbcnt_hi_u32_b32 %0, -1, %0" : "=v"(l)); return l; }
; DI void attn_phase(LAS unsigned char* lds, const int wid, const bf16_t* Q, const bf16_t* Kn, const bf16_t* Kr, const bf16_t* Vt, bf16_t* O, int G, int c) {
;     const int lane = lane_id(), tid = wid * 64 + lane, r16 = lane & 15, qd = lane >> 4;
;     for (int it = 0;; ++it) {
;         const long L = (long)it * G + c; if (L >= 2048) break;
;         const int xcd = (int)(L & 7), idx = (int)(L >> 3), bh = (idx >> 5) * 8 + xcd, qb = idx & 31, b = bh >> 3, h = bh & 7;
;         const size_t tok0 = (size_t)b * SEQ;
;         const int q0 = qb * 256 + wid * 32;
;         bf16x8 qf[2][3];
; #pragma unroll
;         for (int qt = 0; qt < 2; ++qt) { const bf16_t* qp = Q + (tok0 + q0 + 16 * qt + r16) * 768 + h * 96 + 8 * qd;
; #pragma unroll
;           for (int ks = 0; ks < 3; ++ks) qf[qt][ks] = *(const bf16x8*)(qp + 32 * ks); }
;         f32x4 oacc[4][2], sa[4][2], sb[4][2];
;         f32x4 negm0 = {0.f, 0.f, 0.f, 0.f}, negm1 = {0.f, 0.f, 0.f, 0.f};
; #pragma unroll
;         for (int t4 = 0; t4 < 4; ++t4) { oacc[t4][0] = (f32x4){0.f, 0.f, 0.f, 0.f}; oacc[t4][1] = (f32x4){0.f, 0.f, 0.f, 0.f}; }
;         float l0 = 0.f, l1 = 0.f;
;         const int skey = tid >> 3, sch = tid & 7;
;         const int rkey = (tid & 255) >> 2, rch = tid & 3;
;         const bf16_t* gkn = Kn + (tok0 + skey) * 512 + h * 64 + sch * 8;
;         const bf16_t* gkr = Kr + (tok0 + rkey) * 32 + rch * 8;
;         const bf16_t* gvt = Vt + (size_t)(h * 64 + skey) * T + tok0 + sch * 8;
;         const unsigned lkn = skey * KS_STRIDE + sch * 16, lkr = rkey * KS_STRIDE + 128 + rch * 16, lvt = VOFF + skey * VS_STRIDE + (sch >> 2) * 64 + ((sch & 1) * 4 + ((sch >> 1) & 1)) * 8;
.LBB0_856:
	s_mov_b64 s[6:7], s[0:1]
	s_mov_b64 s[8:9], s[0:1]
	s_load_dwordx2 s[6:7], s[6:7], 0xf8
	s_mov_b64 s[10:11], s[0:1]
	s_load_dwordx2 s[8:9], s[8:9], 0xf8
	s_load_dwordx2 s[14:15], s[10:11], 0xf8
	s_mov_b64 s[10:11], s[0:1]
	s_load_dwordx2 s[28:29], s[10:11], 0xf8
	s_mov_b64 s[10:11], s[0:1]
	s_load_dwordx2 s[16:17], s[10:11], 0xf8
	v_mbcnt_lo_u32_b32 v1, -1, 0
	v_mbcnt_hi_u32_b32 v1, -1, v1
	v_mov_b32_e32 v0, 0
	v_ashrrev_i32_e32 v9, 4, v1
	v_lshlrev_b32_e32 v2, 3, v9
	v_ashrrev_i32_e32 v3, 31, v2
	s_waitcnt lgkmcnt(0)
	v_lshl_add_u64 v[2:3], v[2:3], 1, s[6:7]
	s_mov_b64 s[6:7], 0x26cc0000
	v_lshlrev_b32_e32 v4, 4, v1
	v_add_u32_e32 v8, s33, v1
	v_lshl_add_u64 v[158:159], v[2:3], 0, s[6:7]
	v_lshrrev_b32_e32 v3, 3, v1
	v_and_b32_e32 v4, 48, v1
	v_mov_b32_e32 v5, v0
	v_lshrrev_b32_e32 v236, 6, v8
	v_and_b32_e32 v237, 7, v1
	v_and_b32_e32 v238, 15, v1
	v_lshl_or_b32 v160, v236, 3, v237
	v_mul_u32_u24_e32 v243, 0xc00, v236
	v_lshlrev_b32_e32 v244, 4, v1
	v_lshrrev_b32_e32 v239, 4, v160
	v_and_b32_e32 v240, 15, v160
	v_lshlrev_b32_e32 v241, 11, v239
	v_mul_u32_u24_e32 v239, 0xc00, v239
	v_lshlrev_b32_e32 v240, 4, v240
	v_lshl_add_u32 v239, v3, 8, v239
	v_bfe_u32 v242, v3, 2, 1
	v_add_u32_e32 v239, v239, v240
	v_lshl_or_b32 v241, v242, 10, v241
	v_and_b32_e32 v242, 1, v3
	v_or_b32_e32 v241, v241, v240
	v_lshl_or_b32 v241, v242, 9, v241
	v_bfe_u32 v242, v3, 1, 1
	v_add_u32_e32 v243, v243, v244
	v_lshl_or_b32 v241, v242, 3, v241
	v_add_u32_e32 v243, 0x800, v243
	v_lshl_add_u64 v[6:7], s[14:15], 0, v[4:5]
	s_mov_b64 s[6:7], 0x208c0000
	v_lshlrev_b32_e32 v166, 4, v3
	s_movk_i32 s21, 0xd0
	v_lshl_add_u64 v[164:165], v[6:7], 0, s[6:7]
	s_movk_i32 s6, 0x90
	v_lshlrev_b32_e32 v2, 3, v3
	s_movk_i32 s6, 0x100
	v_cmp_gt_i32_e64 s[10:11], s6, v8
	s_movk_i32 s6, 0xff
	s_add_u32 s30, s8, 0x2ccc0000
	v_lshl_or_b32 v162, v236, 4, v238
	v_and_b32_e32 v162, 63, v162
	v_cmp_lt_i32_e64 s[12:13], s6, v8
	v_lshlrev_b32_e32 v8, 2, v9
	s_addc_u32 s31, s9, 0
	v_ashrrev_i32_e32 v9, 31, v8
	s_load_dword s68, s[0:1], 0x108
	s_add_u32 s34, s28, 0x338c0000
	v_and_b32_e32 v156, 15, v1
	v_lshl_add_u64 v[8:9], v[8:9], 1, s[16:17]
	s_mov_b64 s[6:7], 0x3b8c0000
	v_lshl_or_b32 v4, v162, 6, v4
	v_mov_b32_e32 v5, v0
	s_addc_u32 s35, s29, 0
	s_ashr_i32 s33, s18, 31
	v_ashrrev_i32_e32 v161, 31, v160
	v_lshl_add_u64 v[168:169], v[8:9], 0, s[6:7]
	v_lshl_add_u64 v[4:5], s[14:15], 0, v[4:5]
	s_mov_b64 s[6:7], 0x208c6000
	s_mov_b32 s73, s5
	s_cmpk_gt_u32 s5, 0xff
	v_lshl_add_u64 v[170:171], v[4:5], 0, s[6:7]
	v_lshlrev_b64 v[4:5], 10, v[160:161]
	s_mov_b32 s69, s4
	v_readlane_b32 s4, v255, 12
	v_readlane_b32 s70, v255, 4
	v_readlane_b32 s54, v255, 6
	s_mov_b32 s64, s18
	s_mov_b32 s37, 0
	s_cselect_b64 s[38:39], -1, 0
	v_mov_b32_e32 v167, v0
	v_lshl_add_u64 v[172:173], s[8:9], 0, v[4:5]
	v_mov_b64_e32 v[174:175], 0x7ff
	s_movk_i32 s6, 0x600
	s_mov_b64 s[40:41], 0x6000
	s_movk_i32 s7, 0x6000
	v_lshlrev_b32_e32 v176, 1, v2
	s_mov_b32 s8, 0x40c00000
	s_mov_b32 s52, 0x2cd10000
	s_mov_b32 s53, 0
	s_mov_b32 s56, 0x338c0000
	s_mov_b32 s57, 0
	s_mov_b32 s58, 0x2cd20000
	s_mov_b32 s59, 0
	s_mov_b32 s62, 0x2cd30000
	s_mov_b32 s63, 0
	s_mov_b64 s[42:43], 0x100
	s_mov_b64 s[44:45], 0x2000
	s_mov_b64 s[46:47], 0x20000
	v_mov_b32_e32 v196, 0x600
	v_mov_b32_e32 v197, v239
	v_mov_b32_e32 v198, v241
	v_mov_b32_e32 v199, v243
	v_mov_b32_e32 v200, v244
	s_mov_b32 s9, s2
	s_mov_b32 s21, 0
	v_readlane_b32 s5, v255, 13
	v_readlane_b32 s71, v255, 5
	v_readlane_b32 s55, v255, 7
	s_branch .LBB0_859

.LBB0_883:
	ds_read_b128 v[60:63], v201
	ds_read_b128 v[64:67], v201 offset:1024
	ds_read_b128 v[76:79], v201 offset:3072
	ds_read_b128 v[80:83], v201 offset:2048
	ds_read_b128 v[88:91], v201 offset:6144
	ds_read_b128 v[152:155], v201 offset:7168
	ds_read_b128 v[184:187], v201 offset:9216
	ds_read_b128 v[188:191], v201 offset:8192
	s_waitcnt lgkmcnt(7)
	v_mfma_f32_16x16x32_bf16 v[68:71], v[60:63], v[12:15], v[44:47]
	v_mfma_f32_16x16x32_bf16 v[60:63], v[60:63], v[16:19], v[48:51]
	s_waitcnt lgkmcnt(5)
	v_mfma_f32_16x16x32_bf16 v[84:87], v[76:79], v[12:15], v[44:47]
	v_mfma_f32_16x16x32_bf16 v[76:79], v[76:79], v[16:19], v[48:51]
	v_mfma_f32_16x16x32_bf16 v[68:71], v[64:67], v[4:7], v[68:71]
	v_mfma_f32_16x16x32_bf16 v[60:63], v[64:67], v[20:23], v[60:63]
	ds_read_b128 v[64:67], v201 offset:4096
	ds_read_b128 v[204:207], v201 offset:5120
	s_waitcnt lgkmcnt(5)
	v_mfma_f32_16x16x32_bf16 v[180:183], v[88:91], v[12:15], v[44:47]
	v_mfma_f32_16x16x32_bf16 v[88:91], v[88:91], v[16:19], v[48:51]
	s_waitcnt lgkmcnt(3)
	v_mfma_f32_16x16x32_bf16 v[192:195], v[184:187], v[12:15], v[44:47]
	s_waitcnt lgkmcnt(1)
	v_mfma_f32_16x16x32_bf16 v[208:211], v[64:67], v[4:7], v[84:87]
	v_mfma_f32_16x16x32_bf16 v[64:67], v[64:67], v[20:23], v[76:79]
	s_nop 2
	ds_read_b128 v[76:79], v201 offset:10240
	ds_read_b128 v[216:219], v201 offset:11264
	v_mfma_f32_16x16x32_bf16 v[184:187], v[184:187], v[16:19], v[48:51]
	v_mfma_f32_16x16x32_bf16 v[180:183], v[152:155], v[4:7], v[180:183]
	v_mfma_f32_16x16x32_bf16 v[212:215], v[152:155], v[20:23], v[88:91]
	v_exp_f32_e32 v153, v72
	v_exp_f32_e32 v152, v116
	v_exp_f32_e32 v155, v73
	s_waitcnt lgkmcnt(1)
	v_mfma_f32_16x16x32_bf16 v[192:195], v[76:79], v[4:7], v[192:195]
	v_exp_f32_e32 v154, v117
	s_nop 0
	v_cvt_pk_bf16_f32 v116, v152, v154
	v_mfma_f32_16x16x32_bf16 v[220:223], v[76:79], v[20:23], v[184:187]
	v_mfma_f32_16x16x32_bf16 v[84:87], v[80:83], v[8:11], v[68:71]
	s_nop 1
	v_exp_f32_e32 v187, v111
	v_exp_f32_e32 v185, v75
	v_exp_f32_e32 v184, v119
	v_mfma_f32_16x16x32_bf16 v[88:91], v[80:83], v[24:27], v[60:63]
	v_exp_f32_e32 v186, v115
	v_mfma_f32_16x16x32_bf16 v[80:83], v[204:207], v[24:27], v[64:67]
	v_mfma_f32_16x16x32_bf16 v[60:63], v[188:191], v[8:11], v[180:183]
	v_mfma_f32_16x16x32_bf16 v[68:71], v[188:191], v[24:27], v[212:215]
	v_exp_f32_e32 v191, v109
	v_exp_f32_e32 v189, v110
	v_exp_f32_e32 v181, v74
	s_waitcnt lgkmcnt(0)
	v_mfma_f32_16x16x32_bf16 v[64:67], v[216:219], v[8:11], v[192:195]
	v_exp_f32_e32 v180, v118
	v_exp_f32_e32 v190, v113
	v_exp_f32_e32 v188, v114
	v_exp_f32_e32 v193, v108
	ds_read_b128 v[108:111], v200 offset:32768
	v_exp_f32_e32 v192, v112
	v_mfma_f32_16x16x32_bf16 v[76:79], v[204:207], v[8:11], v[208:211]
	ds_read_b128 v[204:207], v200 offset:34816
	s_nop 1
	ds_read_b128 v[208:211], v200 offset:33792
	v_cvt_pk_bf16_f32 v112, v153, v155
	v_cvt_pk_bf16_f32 v113, v181, v185
	v_cvt_pk_bf16_f32 v114, v193, v191
	v_cvt_pk_bf16_f32 v115, v189, v187
	v_cvt_pk_bf16_f32 v117, v180, v184
	v_cvt_pk_bf16_f32 v118, v192, v190
	v_cvt_pk_bf16_f32 v119, v188, v186
	v_mfma_f32_16x16x32_bf16 v[72:75], v[216:219], v[24:27], v[220:223]
	v_exp_f32_e32 v183, v100
	v_exp_f32_e32 v182, v104
	v_exp_f32_e32 v195, v101
	s_waitcnt lgkmcnt(2)
	v_mfma_f32_16x16x32_bf16 v[148:151], v[108:111], v[112:115], v[148:151]
	v_exp_f32_e32 v194, v105
	v_cvt_pk_bf16_f32 v228, v183, v195
	v_mfma_f32_16x16x32_bf16 v[108:111], v[108:111], v[116:119], v[144:147]
	s_nop 2
	ds_read_b128 v[144:147], v200 offset:36864
	ds_read_b128 v[212:215], v200 offset:35840
	v_cvt_pk_bf16_f32 v232, v182, v194
	s_waitcnt lgkmcnt(3)
	v_mfma_f32_16x16x32_bf16 v[216:219], v[204:207], v[112:115], v[140:143]
	s_nop 2
	v_exp_f32_e32 v141, v102
	v_exp_f32_e32 v140, v106
	v_exp_f32_e32 v143, v103
	v_mfma_f32_16x16x32_bf16 v[100:103], v[204:207], v[116:119], v[136:139]
	v_exp_f32_e32 v142, v107
	ds_read_b128 v[104:107], v200 offset:38912
	s_nop 0
	ds_read_b128 v[136:139], v200 offset:37888
	ds_read_b128 v[220:223], v200 offset:39936
	s_waitcnt lgkmcnt(4)
	v_mfma_f32_16x16x32_bf16 v[204:207], v[144:147], v[112:115], v[132:135]
	v_cvt_pk_bf16_f32 v229, v141, v143
	v_cvt_pk_bf16_f32 v233, v140, v142
	s_waitcnt vmcnt(3)
	ds_write_b128 v197, v[32:35] offset:12288
	v_exp_f32_e32 v133, v92
	v_exp_f32_e32 v132, v96
	v_exp_f32_e32 v135, v93
	v_mfma_f32_16x16x32_bf16 v[144:147], v[144:147], v[116:119], v[128:131]
	v_exp_f32_e32 v134, v97
	v_cvt_pk_bf16_f32 v230, v133, v135
	s_nop 0
	v_exp_f32_e32 v129, v94
	s_waitcnt lgkmcnt(3)
; #define LAS __attribute__((address_space(3)))
; #define MFMA16(a_, b_, c_) __builtin_amdgcn_mfma_f32_16x16x32_bf16((a_), (b_), (c_), 0, 0, 0)
; DI void attn_phase(LAS unsigned char* lds, const int wid, const bf16_t* Q, const bf16_t* Kn, const bf16_t* Kr, const bf16_t* Vt, bf16_t* O, int G, int c) {
;     ...
;         u32x4 rkn = *(const u32x4*)gkn, rvt = *(const u32x4*)gvt, rkr = {0u, 0u, 0u, 0u};
;         if (tid < 256) rkr = *(const u32x4*)gkr;
;         *(LAS u32x4*)(lds + lkn) = rkn; *(LAS u32x2*)(lds + lvt) = (u32x2){rvt.x, rvt.y}; *(LAS u32x2*)(lds + lvt + 16) = (u32x2){rvt.z, rvt.w}; if (tid < 256) *(LAS u32x4*)(lds + lkr) = rkr;
;         rkn = *(const u32x4*)(gkn + 64 * 512); if (tid < 256) rkr = *(const u32x4*)(gkr + 64 * 32);
;         *(LAS u32x4*)(lds + KS_BYTES + lkn) = rkn; if (tid < 256) *(LAS u32x4*)(lds + KS_BYTES + lkr) = rkr;
;         __syncthreads();
;         { const LAS unsigned char* kp = lds + r16 * KS_STRIDE + qd * 16;
; #pragma unroll
;           for (int t4 = 0; t4 < 4; ++t4) { sa[t4][0] = negm0; sa[t4][1] = negm1; }
; #pragma unroll
;           for (int ks = 0; ks < 3; ++ks)
; #pragma unroll
;             for (int t4 = 0; t4 < 4; ++t4) { const bf16x8 kf = *(const LAS bf16x8*)(kp + t4 * 16 * KS_STRIDE + ks * 64);
;                 sa[t4][0] = MFMA16(kf, qf[0][ks], sa[t4][0]); sa[t4][1] = MFMA16(kf, qf[1][ks], sa[t4][1]); } }
;         __syncthreads();
;         u32x4 akn = *(const u32x4*)(gkn + (size_t)2 * 64 * 512), avt = *(const u32x4*)(gvt + 64), akr = {0u, 0u, 0u, 0u}, bkn, bkr = {0u, 0u, 0u, 0u}, bvt;
;         if (tid < 256) akr = *(const u32x4*)(gkr + (size_t)2 * 64 * 32);
;         if (wid >= 4) __builtin_amdgcn_s_setprio(1);
;         for (int kt = 0; kt < NKT; kt += 2) {
	v_mfma_f32_16x16x32_bf16 v[224:227], v[104:107], v[112:115], v[124:127]
	v_exp_f32_e32 v128, v98
	v_cvt_pk_bf16_f32 v234, v132, v134
	s_nop 0
	v_exp_f32_e32 v125, v95
	v_exp_f32_e32 v124, v99
	v_mfma_f32_16x16x32_bf16 v[92:95], v[104:107], v[116:119], v[120:123]
	v_cvt_pk_bf16_f32 v231, v129, v125
	v_cvt_pk_bf16_f32 v235, v128, v124
	s_nop 0
	v_mfma_f32_16x16x32_bf16 v[120:123], v[208:211], v[228:231], v[148:151]
	v_mfma_f32_16x16x32_bf16 v[104:107], v[208:211], v[232:235], v[108:111]
	v_mfma_f32_16x16x32_bf16 v[116:119], v[212:215], v[228:231], v[216:219]
	v_mfma_f32_16x16x32_bf16 v[100:103], v[212:215], v[232:235], v[100:103]
	s_waitcnt lgkmcnt(2)
	v_mfma_f32_16x16x32_bf16 v[112:115], v[136:139], v[228:231], v[204:207]
	v_mfma_f32_16x16x32_bf16 v[96:99], v[136:139], v[232:235], v[144:147]
	s_waitcnt lgkmcnt(1)
	v_mfma_f32_16x16x32_bf16 v[108:111], v[220:223], v[228:231], v[224:227]
	v_mfma_f32_16x16x32_bf16 v[92:95], v[220:223], v[232:235], v[92:95]
	s_and_saveexec_b64 s[48:49], s[10:11]
	ds_write_b128 v199, v[36:39] offset:12288
	s_or_b64 exec, exec, s[48:49]
	v_pk_add_f32 v[126:127], v[152:153], 0 op_sel_hi:[1,0]
	v_pk_add_f32 v[130:131], v[154:155], 0 op_sel_hi:[1,0]
	v_pk_add_f32 v[136:137], v[180:181], 0 op_sel_hi:[1,0]
	v_pk_add_f32 v[138:139], v[184:185], 0 op_sel_hi:[1,0]
	v_pk_add_f32 v[126:127], v[192:193], v[126:127]
	v_pk_add_f32 v[130:131], v[190:191], v[130:131]
	v_pk_add_f32 v[136:137], v[188:189], v[136:137]
	v_pk_add_f32 v[138:139], v[186:187], v[138:139]
	v_pk_add_f32 v[126:127], v[182:183], v[126:127]
	v_pk_add_f32 v[130:131], v[194:195], v[130:131]
	v_pk_add_f32 v[136:137], v[140:141], v[136:137]
	v_pk_add_f32 v[138:139], v[142:143], v[138:139]
	v_pk_add_f32 v[126:127], v[132:133], v[126:127]
	v_pk_add_f32 v[130:131], v[134:135], v[130:131]
	v_pk_add_f32 v[128:129], v[128:129], v[136:137]
	v_pk_add_f32 v[124:125], v[124:125], v[138:139]
	v_pk_add_f32 v[126:127], v[126:127], v[130:131]
	v_pk_add_f32 v[124:125], v[128:129], v[124:125]
	s_and_b32 s26, s9, 7
	v_pk_add_f32 v[124:125], v[126:127], v[124:125]
	s_waitcnt vmcnt(2)
	ds_write2_b64 v177, v[40:41], v[42:43] offset1:32
	v_pk_add_f32 v[184:185], v[2:3], v[124:125]
	v_lshl_add_u32 v2, s26, 6, v160
	s_lshl_b32 s26, s26, 7
	v_ashrrev_i32_e32 v3, 31, v2
	s_add_u32 s16, s28, s16
	v_lshlrev_b64 v[2:3], 17, v[2:3]
	s_addc_u32 s17, s29, s17
	v_lshl_add_u64 v[2:3], s[16:17], 0, v[2:3]
	s_lshl_b64 s[16:17], s[14:15], 19
	s_lshl_b64 s[14:15], s[14:15], 23
	s_or_b32 s14, s14, s26
	v_lshl_add_u64 v[180:181], v[170:171], 0, s[16:17]
	v_lshl_add_u64 v[182:183], v[172:173], 0, s[14:15]
	v_max3_f32 v246, v88, v89, v90
	v_max3_f32 v247, v84, v85, v86
	v_max3_f32 v246, v246, v91, v80
	v_max3_f32 v247, v247, v87, v76
	v_max3_f32 v246, v246, v81, v82
	v_max3_f32 v247, v247, v77, v78
	v_max3_f32 v246, v246, v83, v68
	v_max3_f32 v247, v247, v79, v60
	v_max3_f32 v246, v246, v69, v70
	v_max3_f32 v247, v247, v61, v62
	v_max3_f32 v246, v246, v71, v72
	v_max3_f32 v247, v247, v63, v64
	v_max3_f32 v246, v246, v73, v74
	v_max3_f32 v247, v247, v65, v66
	s_mov_b32 s26, 2
	v_add_u32_e32 v252, 0x10000, v198
	v_add_u32_e32 v253, 0x12000, v198
	v_add_u32_e32 v203, 0xc000, v200
	s_waitcnt vmcnt(0)
	ds_write_b128 v197, v[52:55] offset:40960
	s_and_saveexec_b64 s[14:15], s[10:11]
	ds_write_b128 v199, v[28:31] offset:40960
	s_or_b64 exec, exec, s[14:15]
	ds_write2_b64 v252, v[56:57], v[58:59] offset1:32
	s_waitcnt lgkmcnt(0)
	v_lshl_add_u64 v[186:187], v[182:183], 0, v[166:167]
	v_lshl_add_u64 v[52:53], v[186:187], 0, s[52:53]
	global_load_dwordx4 v[52:55], v[52:53], off
	s_and_saveexec_b64 s[14:15], s[10:11]
	s_cbranch_execz .Lattn_pre_skip
	global_load_dwordx4 v[28:31], v[180:181], off offset:-4096
.Lattn_pre_skip:
	s_or_b64 exec, exec, s[14:15]
	v_lshl_add_u64 v[188:189], v[2:3], 0, v[166:167]
	v_lshl_add_u64 v[56:57], v[188:189], 0, s[56:57]
	global_load_dwordx4 v[56:59], v[56:57], off offset:512
	v_add_co_u32_e32 v180, vcc, 0x1000, v180
	s_nop 1
	v_addc_co_u32_e32 v181, vcc, 0, v181, vcc
	s_barrier
	s_branch .LBB0_887
.LBB0_887:
	v_lshl_add_u64 v[186:187], v[182:183], 0, v[166:167]
	v_lshl_add_u64 v[32:33], v[186:187], 0, s[58:59]
	global_load_dwordx4 v[32:35], v[32:33], off
	s_and_saveexec_b64 s[14:15], s[10:11]
	s_cbranch_execz .LBB0_890
	global_load_dwordx4 v[36:39], v[180:181], off offset:-4096

.LBB0_891:
	v_lshl_add_u64 v[188:189], v[2:3], 0, v[166:167]
	v_lshl_add_u64 v[40:41], v[188:189], 0, s[56:57]
	global_load_dwordx4 v[40:43], v[40:41], off offset:640

.LBB0_895:
	ds_read_b128 v[124:127], v201 offset:12288
	ds_read_b128 v[128:131], v201 offset:13312
	ds_read_b128 v[136:139], v201 offset:15360
	ds_read_b128 v[140:143], v201 offset:14336
	ds_read_b128 v[148:151], v201 offset:18432
	ds_read_b128 v[152:155], v201 offset:19456
	ds_read_b128 v[204:207], v201 offset:21504
	ds_read_b128 v[208:211], v201 offset:20480
	s_waitcnt lgkmcnt(7)
	v_mfma_f32_16x16x32_bf16 v[132:135], v[124:127], v[12:15], v[44:47]
	v_exp_f32_e32 v195, v84
	v_exp_f32_e32 v194, v88
	v_mfma_f32_16x16x32_bf16 v[124:127], v[124:127], v[16:19], v[48:51]
	v_exp_f32_e32 v88, v91
	v_exp_f32_e32 v84, v81
	s_waitcnt lgkmcnt(3)
	v_mfma_f32_16x16x32_bf16 v[190:193], v[148:151], v[12:15], v[44:47]
	v_exp_f32_e32 v81, v78
	v_exp_f32_e32 v79, v79
	v_mfma_f32_16x16x32_bf16 v[148:151], v[148:151], v[16:19], v[48:51]
	v_exp_f32_e32 v78, v83
	v_exp_f32_e32 v61, v61
	v_mfma_f32_16x16x32_bf16 v[144:147], v[136:139], v[12:15], v[44:47]
	v_exp_f32_e32 v63, v63
	v_exp_f32_e32 v83, v64
	v_mfma_f32_16x16x32_bf16 v[136:139], v[136:139], v[16:19], v[48:51]
	v_exp_f32_e32 v64, v74
	v_exp_f32_e32 v67, v67
	s_waitcnt lgkmcnt(1)
	v_mfma_f32_16x16x32_bf16 v[212:215], v[204:207], v[12:15], v[44:47]
	v_exp_f32_e32 v250, v90
	v_mfma_f32_16x16x32_bf16 v[204:207], v[204:207], v[16:19], v[48:51]
	v_mfma_f32_16x16x32_bf16 v[132:135], v[128:131], v[4:7], v[132:135]
	v_mfma_f32_16x16x32_bf16 v[124:127], v[128:131], v[20:23], v[124:127]
	ds_read_b128 v[128:131], v201 offset:16384
	ds_read_b128 v[216:219], v201 offset:17408
	v_mfma_f32_16x16x32_bf16 v[220:223], v[152:155], v[20:23], v[148:151]
	v_exp_f32_e32 v249, v85
	v_exp_f32_e32 v248, v89
	v_exp_f32_e32 v251, v86
	ds_read_b128 v[148:151], v201 offset:22528
	ds_read_b128 v[224:227], v201 offset:23552
	s_waitcnt lgkmcnt(3)
	v_mfma_f32_16x16x32_bf16 v[144:147], v[128:131], v[4:7], v[144:147]
	v_exp_f32_e32 v89, v87
	v_exp_f32_e32 v87, v76
	v_mfma_f32_16x16x32_bf16 v[128:131], v[128:131], v[20:23], v[136:139]
	v_exp_f32_e32 v86, v80
	s_waitcnt lgkmcnt(1)
	v_mfma_f32_16x16x32_bf16 v[204:207], v[148:151], v[20:23], v[204:207]
	v_exp_f32_e32 v85, v77
	v_exp_f32_e32 v80, v82
	v_mfma_f32_16x16x32_bf16 v[136:139], v[152:155], v[4:7], v[190:193]
	v_exp_f32_e32 v77, v60
	v_mfma_f32_16x16x32_bf16 v[212:215], v[148:151], v[4:7], v[212:215]
	v_exp_f32_e32 v76, v68
	v_exp_f32_e32 v60, v69
	v_mfma_f32_16x16x32_bf16 v[148:151], v[140:143], v[8:11], v[132:135]
	v_exp_f32_e32 v69, v62
	v_mfma_f32_16x16x32_bf16 v[152:155], v[140:143], v[24:27], v[124:127]
	v_exp_f32_e32 v68, v70
	v_exp_f32_e32 v62, v71
	v_mfma_f32_16x16x32_bf16 v[140:143], v[216:219], v[8:11], v[144:147]
	v_exp_f32_e32 v82, v72
	v_mfma_f32_16x16x32_bf16 v[144:147], v[216:219], v[24:27], v[128:131]
	v_exp_f32_e32 v71, v65
	v_exp_f32_e32 v70, v73
	s_waitcnt lgkmcnt(0)
	v_mfma_f32_16x16x32_bf16 v[128:131], v[224:227], v[24:27], v[204:207]
	v_exp_f32_e32 v65, v66
	ds_read_b128 v[204:207], v200 offset:24576
	v_mfma_f32_16x16x32_bf16 v[132:135], v[208:211], v[8:11], v[136:139]
	v_exp_f32_e32 v66, v75
	v_cvt_pk_bf16_f32 v90, v77, v61
	v_mfma_f32_16x16x32_bf16 v[136:139], v[208:211], v[24:27], v[220:223]
	v_cvt_pk_bf16_f32 v208, v195, v249
	v_cvt_pk_bf16_f32 v209, v251, v89
	v_cvt_pk_bf16_f32 v210, v87, v85
	v_mfma_f32_16x16x32_bf16 v[124:127], v[224:227], v[8:11], v[212:215]
	v_cvt_pk_bf16_f32 v211, v81, v79
	ds_read_b128 v[216:219], v200 offset:26624
	ds_read_b128 v[220:223], v200 offset:25600
	v_cvt_pk_bf16_f32 v212, v194, v248
	v_cvt_pk_bf16_f32 v213, v250, v88
	v_cvt_pk_bf16_f32 v214, v86, v84
	v_cvt_pk_bf16_f32 v215, v80, v78
	s_waitcnt lgkmcnt(2)
	v_mfma_f32_16x16x32_bf16 v[120:123], v[204:207], v[208:211], v[120:123]
	v_cvt_pk_bf16_f32 v91, v69, v63
	v_mfma_f32_16x16x32_bf16 v[104:107], v[204:207], v[212:215], v[104:107]
	ds_read_b128 v[204:207], v200 offset:28672
	ds_read_b128 v[224:227], v200 offset:27648
	s_waitcnt lgkmcnt(3)
	v_mfma_f32_16x16x32_bf16 v[228:231], v[216:219], v[208:211], v[116:119]
	v_mfma_f32_16x16x32_bf16 v[100:103], v[216:219], v[212:215], v[100:103]
	s_nop 1
	ds_read_b128 v[116:119], v200 offset:30720
	ds_read_b128 v[216:219], v200 offset:29696
	s_waitcnt lgkmcnt(3)
	v_mfma_f32_16x16x32_bf16 v[232:235], v[204:207], v[208:211], v[112:115]
	v_mfma_f32_16x16x32_bf16 v[96:99], v[204:207], v[212:215], v[96:99]
	ds_read_b128 v[204:207], v200 offset:31744
	s_waitcnt lgkmcnt(2)
	v_mfma_f32_16x16x32_bf16 v[208:211], v[116:119], v[208:211], v[108:111]
	v_mfma_f32_16x16x32_bf16 v[72:75], v[116:119], v[212:215], v[92:95]
	v_cvt_pk_bf16_f32 v212, v76, v60
	v_cvt_pk_bf16_f32 v213, v68, v62
	v_cvt_pk_bf16_f32 v214, v82, v70
	v_cvt_pk_bf16_f32 v92, v83, v71
	v_cvt_pk_bf16_f32 v93, v65, v67
	v_cvt_pk_bf16_f32 v215, v64, v66
	s_nop 0
	v_mfma_f32_16x16x32_bf16 v[120:123], v[220:223], v[90:93], v[120:123]
	v_mfma_f32_16x16x32_bf16 v[116:119], v[220:223], v[212:215], v[104:107]
	v_max3_f32 v244, v152, v153, v154
	v_max3_f32 v245, v148, v149, v150
	v_mfma_f32_16x16x32_bf16 v[112:115], v[224:227], v[90:93], v[228:231]
	v_max3_f32 v244, v244, v155, v144
	v_max3_f32 v245, v245, v151, v140
	v_mfma_f32_16x16x32_bf16 v[108:111], v[224:227], v[212:215], v[100:103]
	v_max3_f32 v244, v244, v145, v146
	v_max3_f32 v245, v245, v141, v142
	s_waitcnt lgkmcnt(1)
	v_mfma_f32_16x16x32_bf16 v[104:107], v[216:219], v[90:93], v[232:235]
	v_max3_f32 v244, v244, v147, v136
	v_max3_f32 v245, v245, v143, v132
	v_mfma_f32_16x16x32_bf16 v[100:103], v[216:219], v[212:215], v[96:99]
	v_max3_f32 v244, v244, v137, v138
	v_max3_f32 v245, v245, v133, v134
	s_waitcnt lgkmcnt(0)
	v_mfma_f32_16x16x32_bf16 v[92:95], v[204:207], v[90:93], v[208:211]
	v_max3_f32 v244, v244, v139, v128
	v_max3_f32 v245, v245, v135, v124
	v_mfma_f32_16x16x32_bf16 v[96:99], v[204:207], v[212:215], v[72:75]
	v_max3_f32 v244, v244, v129, v130
	v_max3_f32 v245, v245, v125, v126
	s_waitcnt vmcnt(2)
	ds_write_b128 v197, v[52:55] offset:53248
	s_and_saveexec_b64 s[16:17], s[10:11]
	ds_write_b128 v199, v[28:31] offset:53248
	s_or_b64 exec, exec, s[16:17]
.LBB0_899:
	ds_write2_b64 v253, v[56:57], v[58:59] offset1:32
.LBB0_905:
	v_pk_add_f32 v[236:237], v[194:195], v[86:87]
	v_pk_add_f32 v[238:239], v[248:249], v[84:85]
	v_pk_add_f32 v[240:241], v[80:81], v[250:251]
	v_pk_add_f32 v[242:243], v[78:79], v[88:89]
	v_pk_add_f32 v[236:237], v[236:237], v[76:77]
	v_pk_add_f32 v[238:239], v[60:61], v[238:239]
	v_pk_add_f32 v[240:241], v[68:69], v[240:241]
	v_pk_add_f32 v[242:243], v[62:63], v[242:243]
	v_pk_add_f32 v[236:237], v[236:237], v[82:83]
	v_pk_add_f32 v[238:239], v[70:71], v[238:239]
	v_pk_add_f32 v[240:241], v[64:65], v[240:241]
	v_pk_add_f32 v[242:243], v[66:67], v[242:243]
	v_pk_add_f32 v[238:239], v[236:237], v[238:239]
	v_pk_add_f32 v[242:243], v[240:241], v[242:243]
	v_lshl_add_u64 v[52:53], v[186:187], 0, s[62:63]
	global_load_dwordx4 v[52:55], v[52:53], off
	s_and_saveexec_b64 s[16:17], s[10:11]
	s_cbranch_execz .LBB0_902
	global_load_dwordx4 v[28:31], v[180:181], off

.LBB0_903:
	v_lshl_add_u64 v[56:57], v[188:189], 0, s[56:57]
	global_load_dwordx4 v[56:59], v[56:57], off offset:768
	v_max_f32_e32 v60, v244, v131
	v_pk_add_f32 v[238:239], v[238:239], v[242:243]
	v_max_f32_e32 v61, v245, v127
	v_pk_add_f32 v[184:185], v[184:185], v[238:239]
	v_max_f32_e32 v62, v61, v60
	v_cmp_lt_f32_e32 vcc, s8, v62
	s_cbranch_vccz .LBB0_907
	v_and_b32_e32 v63, 64, v202
	v_xor_b32_e32 v62, 16, v202
	v_add_u32_e32 v63, 64, v63
	v_cmp_lt_i32_e32 vcc, v62, v63
	v_xor_b32_e32 v65, 32, v202
	s_nop 0
	v_cndmask_b32_e32 v62, v202, v62, vcc
	v_lshlrev_b32_e32 v62, 2, v62
	ds_bpermute_b32 v64, v62, v61
	ds_bpermute_b32 v62, v62, v60
	v_cmp_lt_i32_e32 vcc, v65, v63
	v_max_f32_e32 v61, v61, v61
	v_max_f32_e32 v60, v60, v60
	s_waitcnt lgkmcnt(1)
	v_max_f32_e32 v64, v64, v64
	v_cndmask_b32_e32 v63, v202, v65, vcc
	v_max_f32_e32 v61, v61, v64
	v_lshlrev_b32_e32 v63, 2, v63
	s_waitcnt lgkmcnt(0)
	v_max_f32_e32 v62, v62, v62
	ds_bpermute_b32 v64, v63, v61
	v_max_f32_e32 v60, v60, v62
	ds_bpermute_b32 v62, v63, v60
	s_waitcnt lgkmcnt(1)
	v_max_f32_e32 v63, v64, v64
	v_max_f32_e32 v61, v61, v63
	s_waitcnt lgkmcnt(0)
	v_max_f32_e32 v62, v62, v62
	v_max_f32_e32 v60, v60, v62
	v_cmp_lt_f32_e32 vcc, s8, v61
	s_nop 1
	v_cndmask_b32_e32 v61, 0, v61, vcc
	v_cmp_lt_f32_e32 vcc, s8, v60
	v_sub_f32_e32 v148, v148, v61
	v_sub_f32_e32 v149, v149, v61
	v_cndmask_b32_e32 v64, 0, v60, vcc
	v_exp_f32_e64 v60, -v61
	v_exp_f32_e64 v62, -v64
	v_sub_f32_e32 v150, v150, v61
	v_sub_f32_e32 v151, v151, v61
	v_sub_f32_e32 v152, v152, v64
	v_pk_mul_f32 v[118:119], v[118:119], v[62:63] op_sel_hi:[1,0]
	v_pk_mul_f32 v[116:117], v[116:117], v[62:63] op_sel_hi:[1,0]
	v_pk_mul_f32 v[110:111], v[110:111], v[62:63] op_sel_hi:[1,0]
	v_pk_mul_f32 v[108:109], v[108:109], v[62:63] op_sel_hi:[1,0]
	v_pk_mul_f32 v[102:103], v[102:103], v[62:63] op_sel_hi:[1,0]
	v_pk_mul_f32 v[100:101], v[100:101], v[62:63] op_sel_hi:[1,0]
	v_pk_mul_f32 v[98:99], v[98:99], v[62:63] op_sel_hi:[1,0]
	v_pk_mul_f32 v[96:97], v[96:97], v[62:63] op_sel_hi:[1,0]
	v_mov_b32_e32 v63, v60
	v_sub_f32_e32 v153, v153, v64
	v_sub_f32_e32 v154, v154, v64
	v_sub_f32_e32 v155, v155, v64
	v_pk_mul_f32 v[122:123], v[122:123], v[60:61] op_sel_hi:[1,0]
	v_pk_mul_f32 v[120:121], v[120:121], v[60:61] op_sel_hi:[1,0]
	v_sub_f32_e32 v140, v140, v61
	v_sub_f32_e32 v141, v141, v61
	v_sub_f32_e32 v142, v142, v61
	v_sub_f32_e32 v143, v143, v61
	v_sub_f32_e32 v144, v144, v64
	v_sub_f32_e32 v145, v145, v64
	v_sub_f32_e32 v146, v146, v64
	v_sub_f32_e32 v147, v147, v64
	v_pk_mul_f32 v[114:115], v[114:115], v[60:61] op_sel_hi:[1,0]
	v_pk_mul_f32 v[112:113], v[112:113], v[60:61] op_sel_hi:[1,0]
	v_sub_f32_e32 v132, v132, v61
	v_sub_f32_e32 v133, v133, v61
	v_sub_f32_e32 v134, v134, v61
	v_sub_f32_e32 v135, v135, v61
	v_sub_f32_e32 v136, v136, v64
	v_sub_f32_e32 v137, v137, v64
	v_sub_f32_e32 v138, v138, v64
	v_sub_f32_e32 v139, v139, v64
	v_pk_mul_f32 v[106:107], v[106:107], v[60:61] op_sel_hi:[1,0]
	v_pk_mul_f32 v[104:105], v[104:105], v[60:61] op_sel_hi:[1,0]
	v_sub_f32_e32 v124, v124, v61
	v_sub_f32_e32 v125, v125, v61
	v_sub_f32_e32 v126, v126, v61
	v_sub_f32_e32 v127, v127, v61
	v_sub_f32_e32 v128, v128, v64
	v_sub_f32_e32 v129, v129, v64
	v_sub_f32_e32 v130, v130, v64
	v_sub_f32_e32 v131, v131, v64
	v_pk_mul_f32 v[94:95], v[94:95], v[60:61] op_sel_hi:[1,0]
	v_pk_mul_f32 v[92:93], v[92:93], v[60:61] op_sel_hi:[1,0]
	v_pk_mul_f32 v[184:185], v[184:185], v[62:63]
	v_sub_f32_e32 v47, v47, v61
	v_sub_f32_e32 v46, v46, v61
	v_sub_f32_e32 v45, v45, v61
	v_sub_f32_e32 v44, v44, v61
	v_sub_f32_e32 v51, v51, v64
	v_sub_f32_e32 v50, v50, v64
	v_sub_f32_e32 v49, v49, v64
	v_sub_f32_e32 v48, v48, v64
.LBB0_907:
	ds_read_b128 v[60:63], v201 offset:40960
	ds_read_b128 v[64:67], v201 offset:41984
	ds_read_b128 v[72:75], v201 offset:44032
	ds_read_b128 v[76:79], v201 offset:43008
	ds_read_b128 v[84:87], v201 offset:47104
	ds_read_b128 v[88:91], v201 offset:48128
	ds_read_b128 v[190:193], v201 offset:50176
	ds_read_b128 v[204:207], v201 offset:49152
	s_waitcnt lgkmcnt(7)
	v_mfma_f32_16x16x32_bf16 v[68:71], v[60:63], v[12:15], v[44:47]
	v_exp_f32_e32 v149, v149
	v_exp_f32_e32 v151, v151
	v_mfma_f32_16x16x32_bf16 v[60:63], v[60:63], v[16:19], v[48:51]
	v_exp_f32_e32 v143, v143
	v_exp_f32_e32 v133, v133
	s_waitcnt lgkmcnt(3)
	v_mfma_f32_16x16x32_bf16 v[186:189], v[84:87], v[12:15], v[44:47]
	v_exp_f32_e32 v135, v135
	v_exp_f32_e32 v127, v127
	v_mfma_f32_16x16x32_bf16 v[84:87], v[84:87], v[16:19], v[48:51]
	v_exp_f32_e32 v249, v148
	v_exp_f32_e32 v248, v152
	v_mfma_f32_16x16x32_bf16 v[80:83], v[72:75], v[12:15], v[44:47]
	v_exp_f32_e32 v148, v153
	v_mfma_f32_16x16x32_bf16 v[72:75], v[72:75], v[16:19], v[48:51]
	v_exp_f32_e32 v153, v150
	v_exp_f32_e32 v152, v154
	s_waitcnt lgkmcnt(1)
	v_mfma_f32_16x16x32_bf16 v[208:211], v[190:193], v[12:15], v[44:47]
	v_exp_f32_e32 v150, v155
	v_mfma_f32_16x16x32_bf16 v[190:193], v[190:193], v[16:19], v[48:51]
	v_exp_f32_e32 v155, v141
	v_exp_f32_e32 v154, v145
	v_mfma_f32_16x16x32_bf16 v[68:71], v[64:67], v[4:7], v[68:71]
	v_exp_f32_e32 v145, v142
	v_mfma_f32_16x16x32_bf16 v[60:63], v[64:67], v[20:23], v[60:63]
	v_exp_f32_e32 v142, v147
	ds_read_b128 v[64:67], v201 offset:45056
	ds_read_b128 v[212:215], v201 offset:46080
	v_mfma_f32_16x16x32_bf16 v[216:219], v[88:91], v[20:23], v[84:87]
	v_exp_f32_e32 v141, v132
	v_exp_f32_e32 v132, v137
	v_exp_f32_e32 v251, v140
	ds_read_b128 v[84:87], v201 offset:51200
	ds_read_b128 v[220:223], v201 offset:52224
	s_waitcnt lgkmcnt(3)
	v_mfma_f32_16x16x32_bf16 v[80:83], v[64:67], v[4:7], v[80:83]
	v_exp_f32_e32 v250, v144
	v_mfma_f32_16x16x32_bf16 v[64:67], v[64:67], v[20:23], v[72:75]
	v_exp_f32_e32 v144, v146
	v_exp_f32_e32 v140, v136
	v_mfma_f32_16x16x32_bf16 v[72:75], v[88:91], v[4:7], v[186:189]
	v_exp_f32_e32 v137, v134
	s_waitcnt lgkmcnt(1)
	v_mfma_f32_16x16x32_bf16 v[188:191], v[84:87], v[20:23], v[190:193]
	v_exp_f32_e32 v136, v138
	v_exp_f32_e32 v134, v139
	v_mfma_f32_16x16x32_bf16 v[88:91], v[76:79], v[24:27], v[60:63]
	v_exp_f32_e32 v139, v124
	v_mfma_f32_16x16x32_bf16 v[60:63], v[204:207], v[8:11], v[72:75]
	v_exp_f32_e32 v138, v128
	s_waitcnt lgkmcnt(0)
	v_mfma_f32_16x16x32_bf16 v[72:75], v[220:223], v[24:27], v[188:191]
	v_exp_f32_e32 v147, v125
	ds_read_b128 v[190:193], v203 offset:16384
	v_mfma_f32_16x16x32_bf16 v[208:211], v[84:87], v[4:7], v[208:211]
	v_exp_f32_e32 v146, v129
	v_mfma_f32_16x16x32_bf16 v[84:87], v[76:79], v[8:11], v[68:71]
	v_exp_f32_e32 v125, v126
	v_mfma_f32_16x16x32_bf16 v[76:79], v[212:215], v[8:11], v[80:83]
	v_exp_f32_e32 v124, v130
	v_mfma_f32_16x16x32_bf16 v[80:83], v[212:215], v[24:27], v[64:67]
	v_exp_f32_e32 v126, v131
	v_mfma_f32_16x16x32_bf16 v[68:71], v[204:207], v[24:27], v[216:219]
	ds_read_b128 v[212:215], v203 offset:18432
	s_nop 1
	ds_read_b128 v[216:219], v203 offset:17408
	v_cvt_pk_bf16_f32 v204, v249, v149
	v_cvt_pk_bf16_f32 v205, v153, v151
	v_mfma_f32_16x16x32_bf16 v[64:67], v[220:223], v[8:11], v[208:211]
	v_cvt_pk_bf16_f32 v206, v251, v155
	v_cvt_pk_bf16_f32 v207, v145, v143
	v_cvt_pk_bf16_f32 v208, v248, v148
	v_cvt_pk_bf16_f32 v209, v152, v150
	v_cvt_pk_bf16_f32 v210, v250, v154
	v_cvt_pk_bf16_f32 v211, v144, v142
	s_waitcnt lgkmcnt(2)
	v_mfma_f32_16x16x32_bf16 v[120:123], v[190:193], v[204:207], v[120:123]
	v_mfma_f32_16x16x32_bf16 v[116:119], v[190:193], v[208:211], v[116:119]
	ds_read_b128 v[190:193], v203 offset:20480
	ds_read_b128 v[220:223], v203 offset:19456
	s_waitcnt lgkmcnt(3)
	v_mfma_f32_16x16x32_bf16 v[112:115], v[212:215], v[204:207], v[112:115]
	v_mfma_f32_16x16x32_bf16 v[108:111], v[212:215], v[208:211], v[108:111]
	ds_read_b128 v[212:215], v203 offset:22528
	ds_read_b128 v[224:227], v203 offset:21504
	ds_read_b128 v[232:235], v203 offset:23552
	s_waitcnt lgkmcnt(4)
	v_mfma_f32_16x16x32_bf16 v[228:231], v[190:193], v[204:207], v[104:107]
	v_mfma_f32_16x16x32_bf16 v[190:193], v[190:193], v[208:211], v[100:103]
	s_waitcnt lgkmcnt(2)
	v_mfma_f32_16x16x32_bf16 v[92:95], v[212:215], v[204:207], v[92:95]
	v_cvt_pk_bf16_f32 v204, v141, v133
	v_cvt_pk_bf16_f32 v205, v137, v135
	v_cvt_pk_bf16_f32 v206, v139, v147
	v_mfma_f32_16x16x32_bf16 v[128:131], v[212:215], v[208:211], v[96:99]
	v_cvt_pk_bf16_f32 v207, v125, v127
	v_cvt_pk_bf16_f32 v208, v140, v132
	v_cvt_pk_bf16_f32 v209, v136, v134
	v_cvt_pk_bf16_f32 v210, v138, v146
	v_cvt_pk_bf16_f32 v211, v124, v126
	v_mfma_f32_16x16x32_bf16 v[120:123], v[216:219], v[204:207], v[120:123]
	s_nop 0
	v_mfma_f32_16x16x32_bf16 v[104:107], v[216:219], v[208:211], v[116:119]
	v_max3_f32 v246, v88, v89, v90
	v_max3_f32 v247, v84, v85, v86
	v_mfma_f32_16x16x32_bf16 v[116:119], v[220:223], v[204:207], v[112:115]
	v_max3_f32 v246, v246, v91, v80
	v_max3_f32 v247, v247, v87, v76
	v_mfma_f32_16x16x32_bf16 v[100:103], v[220:223], v[208:211], v[108:111]
	v_max3_f32 v246, v246, v81, v82
	v_max3_f32 v247, v247, v77, v78
	s_waitcnt lgkmcnt(1)
	v_mfma_f32_16x16x32_bf16 v[112:115], v[224:227], v[204:207], v[228:231]
	v_max3_f32 v246, v246, v83, v68
	v_max3_f32 v247, v247, v79, v60
	v_mfma_f32_16x16x32_bf16 v[96:99], v[224:227], v[208:211], v[190:193]
	v_max3_f32 v246, v246, v69, v70
	v_max3_f32 v247, v247, v61, v62
	s_waitcnt lgkmcnt(0)
	v_mfma_f32_16x16x32_bf16 v[108:111], v[232:235], v[204:207], v[92:95]
	v_max3_f32 v246, v246, v71, v72
	v_max3_f32 v247, v247, v63, v64
	v_mfma_f32_16x16x32_bf16 v[92:95], v[232:235], v[208:211], v[128:131]
	v_max3_f32 v246, v246, v73, v74
	v_max3_f32 v247, v247, v65, v66
	s_waitcnt vmcnt(2)
	ds_write_b128 v197, v[32:35]
	s_and_saveexec_b64 s[16:17], s[10:11]
	ds_write_b128 v199, v[36:39]
	s_or_b64 exec, exec, s[16:17]
.LBB0_911:
	ds_write2_b64 v1, v[40:41], v[42:43] offset1:32
	v_pk_add_f32 v[236:237], v[248:249], v[250:251]
	v_pk_add_f32 v[238:239], v[148:149], v[154:155]
	v_pk_add_f32 v[240:241], v[144:145], v[152:153]
	v_pk_add_f32 v[242:243], v[142:143], v[150:151]
	v_pk_add_f32 v[236:237], v[236:237], v[140:141]
	v_pk_add_f32 v[238:239], v[238:239], v[132:133]
	v_pk_add_f32 v[240:241], v[136:137], v[240:241]
	v_pk_add_f32 v[242:243], v[134:135], v[242:243]
	v_pk_add_f32 v[236:237], v[236:237], v[138:139]
	v_pk_add_f32 v[238:239], v[238:239], v[146:147]
	v_pk_add_f32 v[240:241], v[124:125], v[240:241]
	v_pk_add_f32 v[242:243], v[126:127], v[242:243]
	s_add_i32 s26, s26, 2
	v_pk_add_f32 v[240:241], v[240:241], v[242:243]
	v_pk_add_f32 v[236:237], v[236:237], v[238:239]
	v_lshl_add_u64 v[2:3], v[2:3], 0, s[42:43]
	v_pk_add_f32 v[236:237], v[236:237], v[240:241]
	v_lshl_add_u64 v[180:181], v[180:181], 0, s[44:45]
	v_pk_add_f32 v[184:185], v[184:185], v[236:237]
	v_lshl_add_u64 v[182:183], v[182:183], 0, s[46:47]
	s_cmpk_gt_u32 s26, 0x7f
	s_waitcnt lgkmcnt(0)
	s_barrier
	s_cbranch_scc1 .Lattn_exit
	v_lshl_add_u64 v[186:187], v[182:183], 0, v[166:167]
	v_lshl_add_u64 v[32:33], v[186:187], 0, s[58:59]
	global_load_dwordx4 v[32:35], v[32:33], off
	s_and_saveexec_b64 s[14:15], s[10:11]
	s_cbranch_execz .Lattn2_890
	global_load_dwordx4 v[36:39], v[180:181], off offset:-4096

.Lattn2_895:
	ds_read_b128 v[124:127], v201 offset:53248
	ds_read_b128 v[128:131], v201 offset:54272
	ds_read_b128 v[136:139], v201 offset:56320
	ds_read_b128 v[140:143], v201 offset:55296
	ds_read_b128 v[148:151], v201 offset:59392
	ds_read_b128 v[152:155], v201 offset:60416
	ds_read_b128 v[204:207], v201 offset:62464
	ds_read_b128 v[208:211], v201 offset:61440
	s_waitcnt lgkmcnt(7)
	v_mfma_f32_16x16x32_bf16 v[132:135], v[124:127], v[12:15], v[44:47]
	v_exp_f32_e32 v195, v84
	v_exp_f32_e32 v194, v88
	v_mfma_f32_16x16x32_bf16 v[124:127], v[124:127], v[16:19], v[48:51]
	v_exp_f32_e32 v88, v91
	v_exp_f32_e32 v84, v81
	s_waitcnt lgkmcnt(3)
	v_mfma_f32_16x16x32_bf16 v[190:193], v[148:151], v[12:15], v[44:47]
	v_exp_f32_e32 v81, v78
	v_exp_f32_e32 v79, v79
	v_mfma_f32_16x16x32_bf16 v[148:151], v[148:151], v[16:19], v[48:51]
	v_exp_f32_e32 v78, v83
	v_exp_f32_e32 v61, v61
	v_mfma_f32_16x16x32_bf16 v[144:147], v[136:139], v[12:15], v[44:47]
	v_exp_f32_e32 v63, v63
	v_exp_f32_e32 v83, v64
	v_mfma_f32_16x16x32_bf16 v[136:139], v[136:139], v[16:19], v[48:51]
	v_exp_f32_e32 v64, v74
	v_exp_f32_e32 v67, v67
	s_waitcnt lgkmcnt(1)
	v_mfma_f32_16x16x32_bf16 v[212:215], v[204:207], v[12:15], v[44:47]
	v_exp_f32_e32 v250, v90
	v_mfma_f32_16x16x32_bf16 v[204:207], v[204:207], v[16:19], v[48:51]
	v_mfma_f32_16x16x32_bf16 v[132:135], v[128:131], v[4:7], v[132:135]
	v_mfma_f32_16x16x32_bf16 v[124:127], v[128:131], v[20:23], v[124:127]
	ds_read_b128 v[128:131], v201 offset:57344
	ds_read_b128 v[216:219], v201 offset:58368
	v_mfma_f32_16x16x32_bf16 v[220:223], v[152:155], v[20:23], v[148:151]
	v_exp_f32_e32 v249, v85
	v_exp_f32_e32 v248, v89
	v_exp_f32_e32 v251, v86
	ds_read_b128 v[148:151], v201 offset:63488
	ds_read_b128 v[224:227], v201 offset:64512
	s_waitcnt lgkmcnt(3)
	v_mfma_f32_16x16x32_bf16 v[144:147], v[128:131], v[4:7], v[144:147]
	v_exp_f32_e32 v89, v87
	v_exp_f32_e32 v87, v76
	v_mfma_f32_16x16x32_bf16 v[128:131], v[128:131], v[20:23], v[136:139]
	v_exp_f32_e32 v86, v80
	s_waitcnt lgkmcnt(1)
	v_mfma_f32_16x16x32_bf16 v[204:207], v[148:151], v[20:23], v[204:207]
	v_exp_f32_e32 v85, v77
	v_exp_f32_e32 v80, v82
	v_mfma_f32_16x16x32_bf16 v[136:139], v[152:155], v[4:7], v[190:193]
	v_exp_f32_e32 v77, v60
	v_mfma_f32_16x16x32_bf16 v[212:215], v[148:151], v[4:7], v[212:215]
	v_exp_f32_e32 v76, v68
	v_exp_f32_e32 v60, v69
	v_mfma_f32_16x16x32_bf16 v[148:151], v[140:143], v[8:11], v[132:135]
	v_exp_f32_e32 v69, v62
	v_mfma_f32_16x16x32_bf16 v[152:155], v[140:143], v[24:27], v[124:127]
	v_exp_f32_e32 v68, v70
	v_exp_f32_e32 v62, v71
	v_mfma_f32_16x16x32_bf16 v[140:143], v[216:219], v[8:11], v[144:147]
	v_exp_f32_e32 v82, v72
	v_mfma_f32_16x16x32_bf16 v[144:147], v[216:219], v[24:27], v[128:131]
	v_exp_f32_e32 v71, v65
	v_exp_f32_e32 v70, v73
	s_waitcnt lgkmcnt(0)
	v_mfma_f32_16x16x32_bf16 v[128:131], v[224:227], v[24:27], v[204:207]
	v_exp_f32_e32 v65, v66
	ds_read_b128 v[204:207], v203 offset:24576
	v_mfma_f32_16x16x32_bf16 v[132:135], v[208:211], v[8:11], v[136:139]
	v_exp_f32_e32 v66, v75
	v_cvt_pk_bf16_f32 v90, v77, v61
	v_mfma_f32_16x16x32_bf16 v[136:139], v[208:211], v[24:27], v[220:223]
	v_cvt_pk_bf16_f32 v208, v195, v249
	v_cvt_pk_bf16_f32 v209, v251, v89
	v_cvt_pk_bf16_f32 v210, v87, v85
	v_mfma_f32_16x16x32_bf16 v[124:127], v[224:227], v[8:11], v[212:215]
	v_cvt_pk_bf16_f32 v211, v81, v79
	ds_read_b128 v[216:219], v203 offset:26624
	ds_read_b128 v[220:223], v203 offset:25600
	v_cvt_pk_bf16_f32 v212, v194, v248
	v_cvt_pk_bf16_f32 v213, v250, v88
	v_cvt_pk_bf16_f32 v214, v86, v84
	v_cvt_pk_bf16_f32 v215, v80, v78
	s_waitcnt lgkmcnt(2)
	v_mfma_f32_16x16x32_bf16 v[120:123], v[204:207], v[208:211], v[120:123]
	v_cvt_pk_bf16_f32 v91, v69, v63
	v_mfma_f32_16x16x32_bf16 v[104:107], v[204:207], v[212:215], v[104:107]
	ds_read_b128 v[204:207], v203 offset:28672
	ds_read_b128 v[224:227], v203 offset:27648
	s_waitcnt lgkmcnt(3)
	v_mfma_f32_16x16x32_bf16 v[228:231], v[216:219], v[208:211], v[116:119]
	v_mfma_f32_16x16x32_bf16 v[100:103], v[216:219], v[212:215], v[100:103]
	s_nop 1
	ds_read_b128 v[116:119], v203 offset:30720
	ds_read_b128 v[216:219], v203 offset:29696
	s_waitcnt lgkmcnt(3)
	v_mfma_f32_16x16x32_bf16 v[232:235], v[204:207], v[208:211], v[112:115]
	v_mfma_f32_16x16x32_bf16 v[96:99], v[204:207], v[212:215], v[96:99]
	ds_read_b128 v[204:207], v203 offset:31744
	s_waitcnt lgkmcnt(2)
	v_mfma_f32_16x16x32_bf16 v[208:211], v[116:119], v[208:211], v[108:111]
	v_mfma_f32_16x16x32_bf16 v[72:75], v[116:119], v[212:215], v[92:95]
	v_cvt_pk_bf16_f32 v212, v76, v60
	v_cvt_pk_bf16_f32 v213, v68, v62
	v_cvt_pk_bf16_f32 v214, v82, v70
	v_cvt_pk_bf16_f32 v92, v83, v71
	v_cvt_pk_bf16_f32 v93, v65, v67
	v_cvt_pk_bf16_f32 v215, v64, v66
	s_nop 0
	v_mfma_f32_16x16x32_bf16 v[120:123], v[220:223], v[90:93], v[120:123]
	v_mfma_f32_16x16x32_bf16 v[116:119], v[220:223], v[212:215], v[104:107]
	v_max3_f32 v244, v152, v153, v154
	v_max3_f32 v245, v148, v149, v150
	v_mfma_f32_16x16x32_bf16 v[112:115], v[224:227], v[90:93], v[228:231]
	v_max3_f32 v244, v244, v155, v144
	v_max3_f32 v245, v245, v151, v140
	v_mfma_f32_16x16x32_bf16 v[108:111], v[224:227], v[212:215], v[100:103]
	v_max3_f32 v244, v244, v145, v146
	v_max3_f32 v245, v245, v141, v142
	s_waitcnt lgkmcnt(1)
	v_mfma_f32_16x16x32_bf16 v[104:107], v[216:219], v[90:93], v[232:235]
	v_max3_f32 v244, v244, v147, v136
	v_max3_f32 v245, v245, v143, v132
	v_mfma_f32_16x16x32_bf16 v[100:103], v[216:219], v[212:215], v[96:99]
	v_max3_f32 v244, v244, v137, v138
	v_max3_f32 v245, v245, v133, v134
	s_waitcnt lgkmcnt(0)
	v_mfma_f32_16x16x32_bf16 v[92:95], v[204:207], v[90:93], v[208:211]
	v_max3_f32 v244, v244, v139, v128
	v_max3_f32 v245, v245, v135, v124
	v_mfma_f32_16x16x32_bf16 v[96:99], v[204:207], v[212:215], v[72:75]
	v_max3_f32 v244, v244, v129, v130
	v_max3_f32 v245, v245, v125, v126
	s_waitcnt vmcnt(2)
	ds_write_b128 v197, v[52:55] offset:12288
	s_and_saveexec_b64 s[16:17], s[10:11]
	ds_write_b128 v199, v[28:31] offset:12288
	s_or_b64 exec, exec, s[16:17]
.Lattn2_899:
	ds_write2_b64 v177, v[56:57], v[58:59] offset1:32

.Lattn2_907:
	ds_read_b128 v[60:63], v201
	ds_read_b128 v[64:67], v201 offset:1024
	ds_read_b128 v[72:75], v201 offset:3072
	ds_read_b128 v[76:79], v201 offset:2048
	ds_read_b128 v[84:87], v201 offset:6144
	ds_read_b128 v[88:91], v201 offset:7168
	ds_read_b128 v[190:193], v201 offset:9216
	ds_read_b128 v[204:207], v201 offset:8192
	s_waitcnt lgkmcnt(7)
	v_mfma_f32_16x16x32_bf16 v[68:71], v[60:63], v[12:15], v[44:47]
	v_exp_f32_e32 v149, v149
	v_exp_f32_e32 v151, v151
	v_mfma_f32_16x16x32_bf16 v[60:63], v[60:63], v[16:19], v[48:51]
	v_exp_f32_e32 v143, v143
	v_exp_f32_e32 v133, v133
	s_waitcnt lgkmcnt(3)
	v_mfma_f32_16x16x32_bf16 v[186:189], v[84:87], v[12:15], v[44:47]
	v_exp_f32_e32 v135, v135
	v_exp_f32_e32 v127, v127
	v_mfma_f32_16x16x32_bf16 v[84:87], v[84:87], v[16:19], v[48:51]
	v_exp_f32_e32 v249, v148
	v_exp_f32_e32 v248, v152
	v_mfma_f32_16x16x32_bf16 v[80:83], v[72:75], v[12:15], v[44:47]
	v_exp_f32_e32 v148, v153
	v_mfma_f32_16x16x32_bf16 v[72:75], v[72:75], v[16:19], v[48:51]
	v_exp_f32_e32 v153, v150
	v_exp_f32_e32 v152, v154
	s_waitcnt lgkmcnt(1)
	v_mfma_f32_16x16x32_bf16 v[208:211], v[190:193], v[12:15], v[44:47]
	v_exp_f32_e32 v150, v155
	v_mfma_f32_16x16x32_bf16 v[190:193], v[190:193], v[16:19], v[48:51]
	v_exp_f32_e32 v155, v141
	v_exp_f32_e32 v154, v145
	v_mfma_f32_16x16x32_bf16 v[68:71], v[64:67], v[4:7], v[68:71]
	v_exp_f32_e32 v145, v142
	v_mfma_f32_16x16x32_bf16 v[60:63], v[64:67], v[20:23], v[60:63]
	v_exp_f32_e32 v142, v147
	ds_read_b128 v[64:67], v201 offset:4096
	ds_read_b128 v[212:215], v201 offset:5120
	v_mfma_f32_16x16x32_bf16 v[216:219], v[88:91], v[20:23], v[84:87]
	v_exp_f32_e32 v141, v132
	v_exp_f32_e32 v132, v137
	v_exp_f32_e32 v251, v140
	ds_read_b128 v[84:87], v201 offset:10240
	ds_read_b128 v[220:223], v201 offset:11264
	s_waitcnt lgkmcnt(3)
	v_mfma_f32_16x16x32_bf16 v[80:83], v[64:67], v[4:7], v[80:83]
	v_exp_f32_e32 v250, v144
	v_mfma_f32_16x16x32_bf16 v[64:67], v[64:67], v[20:23], v[72:75]
	v_exp_f32_e32 v144, v146
	v_exp_f32_e32 v140, v136
	v_mfma_f32_16x16x32_bf16 v[72:75], v[88:91], v[4:7], v[186:189]
	v_exp_f32_e32 v137, v134
	s_waitcnt lgkmcnt(1)
	v_mfma_f32_16x16x32_bf16 v[188:191], v[84:87], v[20:23], v[190:193]
	v_exp_f32_e32 v136, v138
	v_exp_f32_e32 v134, v139
	v_mfma_f32_16x16x32_bf16 v[88:91], v[76:79], v[24:27], v[60:63]
	v_exp_f32_e32 v139, v124
	v_mfma_f32_16x16x32_bf16 v[60:63], v[204:207], v[8:11], v[72:75]
	v_exp_f32_e32 v138, v128
	s_waitcnt lgkmcnt(0)
	v_mfma_f32_16x16x32_bf16 v[72:75], v[220:223], v[24:27], v[188:191]
	v_exp_f32_e32 v147, v125
	ds_read_b128 v[190:193], v200 offset:32768
	v_mfma_f32_16x16x32_bf16 v[208:211], v[84:87], v[4:7], v[208:211]
	v_exp_f32_e32 v146, v129
	v_mfma_f32_16x16x32_bf16 v[84:87], v[76:79], v[8:11], v[68:71]
	v_exp_f32_e32 v125, v126
	v_mfma_f32_16x16x32_bf16 v[76:79], v[212:215], v[8:11], v[80:83]
	v_exp_f32_e32 v124, v130
	v_mfma_f32_16x16x32_bf16 v[80:83], v[212:215], v[24:27], v[64:67]
	v_exp_f32_e32 v126, v131
	v_mfma_f32_16x16x32_bf16 v[68:71], v[204:207], v[24:27], v[216:219]
	ds_read_b128 v[212:215], v200 offset:34816
	s_nop 1
	ds_read_b128 v[216:219], v200 offset:33792
	v_cvt_pk_bf16_f32 v204, v249, v149
	v_cvt_pk_bf16_f32 v205, v153, v151
	v_mfma_f32_16x16x32_bf16 v[64:67], v[220:223], v[8:11], v[208:211]
	v_cvt_pk_bf16_f32 v206, v251, v155
	v_cvt_pk_bf16_f32 v207, v145, v143
	v_cvt_pk_bf16_f32 v208, v248, v148
	v_cvt_pk_bf16_f32 v209, v152, v150
	v_cvt_pk_bf16_f32 v210, v250, v154
	v_cvt_pk_bf16_f32 v211, v144, v142
	s_waitcnt lgkmcnt(2)
	v_mfma_f32_16x16x32_bf16 v[120:123], v[190:193], v[204:207], v[120:123]
	v_mfma_f32_16x16x32_bf16 v[116:119], v[190:193], v[208:211], v[116:119]
	ds_read_b128 v[190:193], v200 offset:36864
	ds_read_b128 v[220:223], v200 offset:35840
	s_waitcnt lgkmcnt(3)
	v_mfma_f32_16x16x32_bf16 v[112:115], v[212:215], v[204:207], v[112:115]
	v_mfma_f32_16x16x32_bf16 v[108:111], v[212:215], v[208:211], v[108:111]
	ds_read_b128 v[212:215], v200 offset:38912
	ds_read_b128 v[224:227], v200 offset:37888
	ds_read_b128 v[232:235], v200 offset:39936
	s_waitcnt lgkmcnt(4)
	v_mfma_f32_16x16x32_bf16 v[228:231], v[190:193], v[204:207], v[104:107]
	v_mfma_f32_16x16x32_bf16 v[190:193], v[190:193], v[208:211], v[100:103]
	s_waitcnt lgkmcnt(2)
	v_mfma_f32_16x16x32_bf16 v[92:95], v[212:215], v[204:207], v[92:95]
	v_cvt_pk_bf16_f32 v204, v141, v133
	v_cvt_pk_bf16_f32 v205, v137, v135
	v_cvt_pk_bf16_f32 v206, v139, v147
	v_mfma_f32_16x16x32_bf16 v[128:131], v[212:215], v[208:211], v[96:99]
	v_cvt_pk_bf16_f32 v207, v125, v127
	v_cvt_pk_bf16_f32 v208, v140, v132
	v_cvt_pk_bf16_f32 v209, v136, v134
	v_cvt_pk_bf16_f32 v210, v138, v146
	v_cvt_pk_bf16_f32 v211, v124, v126
	v_mfma_f32_16x16x32_bf16 v[120:123], v[216:219], v[204:207], v[120:123]
	s_nop 0
	v_mfma_f32_16x16x32_bf16 v[104:107], v[216:219], v[208:211], v[116:119]
	v_max3_f32 v246, v88, v89, v90
	v_max3_f32 v247, v84, v85, v86
	v_mfma_f32_16x16x32_bf16 v[116:119], v[220:223], v[204:207], v[112:115]
	v_max3_f32 v246, v246, v91, v80
	v_max3_f32 v247, v247, v87, v76
	v_mfma_f32_16x16x32_bf16 v[100:103], v[220:223], v[208:211], v[108:111]
	v_max3_f32 v246, v246, v81, v82
	v_max3_f32 v247, v247, v77, v78
	s_waitcnt lgkmcnt(1)
	v_mfma_f32_16x16x32_bf16 v[112:115], v[224:227], v[204:207], v[228:231]
	v_max3_f32 v246, v246, v83, v68
	v_max3_f32 v247, v247, v79, v60
	v_mfma_f32_16x16x32_bf16 v[96:99], v[224:227], v[208:211], v[190:193]
	v_max3_f32 v246, v246, v69, v70
	v_max3_f32 v247, v247, v61, v62
	s_waitcnt lgkmcnt(0)
	v_mfma_f32_16x16x32_bf16 v[108:111], v[232:235], v[204:207], v[92:95]
	v_max3_f32 v246, v246, v71, v72
	v_max3_f32 v247, v247, v63, v64
	v_mfma_f32_16x16x32_bf16 v[92:95], v[232:235], v[208:211], v[128:131]
	v_max3_f32 v246, v246, v73, v74
	v_max3_f32 v247, v247, v65, v66
	s_waitcnt vmcnt(2)
	ds_write_b128 v197, v[32:35] offset:40960
	s_and_saveexec_b64 s[16:17], s[10:11]
	ds_write_b128 v199, v[36:39] offset:40960
	s_or_b64 exec, exec, s[16:17]
.Lattn2_911:
	ds_write2_b64 v252, v[40:41], v[42:43] offset1:32
	v_pk_add_f32 v[236:237], v[248:249], v[250:251]
	v_pk_add_f32 v[238:239], v[148:149], v[154:155]
	v_pk_add_f32 v[240:241], v[144:145], v[152:153]
	v_pk_add_f32 v[242:243], v[142:143], v[150:151]
	v_pk_add_f32 v[236:237], v[236:237], v[140:141]
	v_pk_add_f32 v[238:239], v[238:239], v[132:133]
	v_pk_add_f32 v[240:241], v[136:137], v[240:241]
	v_pk_add_f32 v[242:243], v[134:135], v[242:243]
	v_pk_add_f32 v[236:237], v[236:237], v[138:139]
	v_pk_add_f32 v[238:239], v[238:239], v[146:147]
	v_pk_add_f32 v[240:241], v[124:125], v[240:241]
	v_pk_add_f32 v[242:243], v[126:127], v[242:243]
	s_add_i32 s26, s26, 2
	v_pk_add_f32 v[240:241], v[240:241], v[242:243]
	v_pk_add_f32 v[236:237], v[236:237], v[238:239]
	v_lshl_add_u64 v[2:3], v[2:3], 0, s[42:43]
	v_pk_add_f32 v[236:237], v[236:237], v[240:241]
	v_lshl_add_u64 v[180:181], v[180:181], 0, s[44:45]
	v_pk_add_f32 v[184:185], v[184:185], v[236:237]
	v_lshl_add_u64 v[182:183], v[182:183], 0, s[46:47]
	s_cmpk_gt_u32 s26, 0x7f
	s_waitcnt lgkmcnt(0)
	s_barrier
	s_cbranch_scc0 .LBB0_887
